# seam trims 2: + sub-LN gain load issued with the first preamble round, DA->SB workgroup barrier no longer drains the output stores
# baseline (speedup 1.0000x reference)
; #define LAS __attribute__((address_space(3)))
; __device__ __forceinline__ void da_phase(LAS unsigned char* lds, const GAS f16* __restrict__ kv, const GAS f16* __restrict__ qg, GAS f16* __restrict__ mixed, int vcu, int G, ...
;     ...
;     if (tid < 128) ((LAS float*)(lds + DA_SUBG))[tid] = subg[tid];
; __global__ void __launch_bounds__(NWAVES * 64, 2) hybrid_fwd(Args args) {
;     ...
;             const float sa = att::wave_sum(lq1[l * 64 + lane] * lk1[l * 64 + lane]), sb = att::wave_sum(lq2[l * 64 + lane] * lk2[l * 64 + lane]);
;             const float lam_init = 0.8f - 0.6f * __expf(-0.3f * (float)l);
;             const float lam = __expf(sa) - __expf(sb) + lam_init;
;             const float mgq = att::wave_max(fabsf(q_norm_g[l * 64 + lane])), mgk = att::wave_max(fabsf(k_norm_g[l * 64 + lane]));
.LBB0_476:
	s_mov_b64 s[88:89], s[48:49]
	v_or_b32_e32 v2, s22, v1
	v_readlane_b32 s36, v252, 9
	v_lshlrev_b64 v[4:5], 2, v[2:3]
	v_readlane_b32 s48, v252, 21
	v_readlane_b32 s49, v252, 22
	v_readlane_b32 s50, v252, 23
	v_readlane_b32 s51, v252, 24
	v_lshl_add_u64 v[6:7], s[48:49], 0, v[4:5]
	global_load_dword v2, v[6:7], off
	v_lshl_add_u64 v[6:7], s[50:51], 0, v[4:5]
	global_load_dword v6, v[6:7], off
	v_and_b32_e32 v8, 64, v213
	v_add_u32_e32 v8, 64, v8
	v_xor_b32_e32 v9, 1, v213
	v_cmp_lt_i32_e32 vcc, v9, v8
	v_readlane_b32 s44, v252, 17
	v_readlane_b32 s45, v252, 18
	v_cndmask_b32_e32 v9, v213, v9, vcc
	v_lshlrev_b32_e32 v12, 2, v9
	v_readlane_b32 s46, v252, 19
	v_readlane_b32 s47, v252, 20
	v_lshl_add_u64 v[10:11], s[44:45], 0, v[4:5]
	v_lshl_add_u64 v[14:15], s[92:93], 0, v[4:5]
	global_load_dword v246, v[14:15], off
	v_lshl_add_u64 v[14:15], s[94:95], 0, v[4:5]
	global_load_dword v247, v[14:15], off
	v_lshl_add_u64 v[14:15], s[46:47], 0, v[4:5]
	global_load_dword v248, v[14:15], off
	global_load_dword v249, v[10:11], off
	v_mov_b32_e32 v132, v0
	s_lshl_b32 s32, s76, 9
	v_and_b32_e32 v14, 0x7f, v132
	v_lshlrev_b32_e32 v14, 2, v14
	v_add_u32_e32 v14, s32, v14
	global_load_dword v254, v14, s[96:97]
	s_movk_i32 s1, 0x80
	v_readlane_b32 s37, v252, 10
	v_readlane_b32 s38, v252, 11
	v_readlane_b32 s39, v252, 12
	v_readlane_b32 s40, v252, 13
	v_readlane_b32 s41, v252, 14
	v_readlane_b32 s42, v252, 15
	v_readlane_b32 s43, v252, 16
	s_waitcnt vmcnt(0)
	v_mul_f32_e32 v7, v2, v6
	ds_bpermute_b32 v7, v12, v7
	s_waitcnt lgkmcnt(0)
	v_fmac_f32_e32 v7, v2, v6
	v_xor_b32_e32 v2, 2, v213
	v_cmp_lt_i32_e32 vcc, v2, v8
	v_xor_b32_e32 v6, 4, v213
	s_nop 0
	v_cndmask_b32_e32 v2, v213, v2, vcc
	v_lshlrev_b32_e32 v13, 2, v2
	ds_bpermute_b32 v2, v13, v7
	v_cmp_lt_i32_e32 vcc, v6, v8
	s_waitcnt lgkmcnt(0)
	v_add_f32_e32 v2, v7, v2
	v_cndmask_b32_e32 v6, v213, v6, vcc
	v_lshlrev_b32_e32 v14, 2, v6
	ds_bpermute_b32 v6, v14, v2
	s_waitcnt lgkmcnt(0)
	v_add_f32_e32 v2, v2, v6
	v_xor_b32_e32 v6, 8, v213
	v_cmp_lt_i32_e32 vcc, v6, v8
	s_nop 1
	v_cndmask_b32_e32 v6, v213, v6, vcc
	v_lshlrev_b32_e32 v15, 2, v6
	ds_bpermute_b32 v6, v15, v2
	s_waitcnt lgkmcnt(0)
	v_add_f32_e32 v2, v2, v6
	v_xor_b32_e32 v6, 16, v213
	v_cmp_lt_i32_e32 vcc, v6, v8
	s_nop 1
	v_cndmask_b32_e32 v6, v213, v6, vcc
	v_lshlrev_b32_e32 v16, 2, v6
	ds_bpermute_b32 v6, v16, v2
	s_waitcnt lgkmcnt(0)
	v_add_f32_e32 v2, v2, v6
	v_xor_b32_e32 v6, 32, v213
	v_cmp_lt_i32_e32 vcc, v6, v8
	v_cndmask_b32_e32 v6, v213, v6, vcc
	v_lshlrev_b32_e32 v17, 2, v6
	ds_bpermute_b32 v6, v17, v2
	s_waitcnt vmcnt(0)
	v_mul_f32_e32 v9, v246, v247
	ds_bpermute_b32 v9, v12, v9
	s_waitcnt lgkmcnt(0)
	v_and_b32_e32 v5, 0x7fffffff, v248
	ds_bpermute_b32 v5, v12, v5
	v_max_f32_e64 v4, |v248|, |v248|
	v_fmac_f32_e32 v9, v246, v247
	ds_bpermute_b32 v7, v13, v9
	s_waitcnt lgkmcnt(1)
	v_max_f32_e32 v5, v5, v5
	v_max_f32_e32 v4, v4, v5
	ds_bpermute_b32 v5, v13, v4
	s_waitcnt lgkmcnt(1)
	v_add_f32_e32 v7, v9, v7
	ds_bpermute_b32 v8, v14, v7
	s_waitcnt lgkmcnt(0)
	v_max_f32_e32 v5, v5, v5
	v_max_f32_e32 v4, v4, v5
	ds_bpermute_b32 v5, v14, v4
	s_waitcnt lgkmcnt(0)
	v_add_f32_e32 v7, v7, v8
	ds_bpermute_b32 v8, v15, v7
	s_barrier
	v_max_f32_e32 v5, v5, v5
	v_max_f32_e32 v4, v4, v5
	ds_bpermute_b32 v5, v15, v4
	s_waitcnt lgkmcnt(0)
	v_add_f32_e32 v7, v7, v8
	ds_bpermute_b32 v8, v16, v7
	s_waitcnt lgkmcnt(0)
	v_max_f32_e32 v5, v5, v5
	v_max_f32_e32 v4, v4, v5
	ds_bpermute_b32 v5, v16, v4
	v_add_f32_e32 v7, v7, v8
	ds_bpermute_b32 v8, v17, v7
	v_readfirstlane_b32 s0, v132
	v_cmp_gt_i32_e32 vcc, s1, v132
	s_waitcnt lgkmcnt(0)
	v_max_f32_e32 v5, v5, v5
	v_max_f32_e32 v4, v4, v5
	ds_bpermute_b32 v5, v17, v4
	s_waitcnt vmcnt(0)
	v_and_b32_e32 v10, 0x7fffffff, v249
	ds_bpermute_b32 v10, v12, v10
	v_max_f32_e64 v9, |v249|, |v249|
	s_waitcnt lgkmcnt(0)
	v_max_f32_e32 v10, v10, v10
	v_max_f32_e32 v9, v9, v10
	ds_bpermute_b32 v10, v13, v9
	s_waitcnt lgkmcnt(0)
	v_max_f32_e32 v10, v10, v10
	v_max_f32_e32 v9, v9, v10
	ds_bpermute_b32 v10, v14, v9
	s_waitcnt lgkmcnt(0)
	v_max_f32_e32 v10, v10, v10
	v_max_f32_e32 v9, v9, v10
	ds_bpermute_b32 v10, v15, v9
	s_waitcnt lgkmcnt(0)
	v_max_f32_e32 v10, v10, v10
	v_max_f32_e32 v9, v9, v10
	ds_bpermute_b32 v10, v16, v9
	s_waitcnt lgkmcnt(0)
	v_max_f32_e32 v10, v10, v10
	v_max_f32_e32 v9, v9, v10
	ds_bpermute_b32 v10, v17, v9
	s_and_saveexec_b64 s[4:5], vcc
	s_cbranch_execz .LBB0_478
	s_lshl_b32 s80, s76, 7
	s_lshl_b64 s[6:7], s[80:81], 2
	s_add_u32 s6, s96, s6
	s_addc_u32 s7, s97, s7
	v_ashrrev_i32_e32 v133, 31, v132
	v_lshl_add_u64 v[12:13], v[132:133], 2, s[6:7]
	v_lshl_add_u32 v11, v132, 2, 0
	v_add_u32_e32 v11, 0x24400, v11
	s_waitcnt vmcnt(0)
	ds_write_b32 v11, v254

; #define WAIT_BAR(N) asm volatile("s_waitcnt vmcnt(" #N ") lgkmcnt(0)\n\ts_barrier" ::: "memory")
; __device__ __forceinline__ void da_phase(LAS unsigned char* lds, const GAS f16* __restrict__ kv, const GAS f16* __restrict__ qg, GAS f16* __restrict__ mixed, int vcu, int G, ...
;     ...
;     WAIT_BAR(0);
.LBB0_530:
	s_waitcnt lgkmcnt(0)
	s_barrier
	v_readlane_b32 s23, v251, 63
